# barrier: non-leaders invalidate L1 before polling; XCD leader invalidates L2 right after its write-back (all local CUs parked), no post-release invalidate
# baseline (speedup 1.0000x reference)
.LBB0_38:
	s_or_b64 exec, exec, s[2:3]
	v_cvt_f32_u32_e32 v4, v2
	s_waitcnt vmcnt(0)
	v_readfirstlane_b32 s2, v3
	v_sub_u32_e32 v3, 0, v2
	v_rcp_iflag_f32_e32 v4, v4
	v_add_u32_e32 v5, s2, v1
	v_mul_f32_e32 v4, 0x4f7ffffe, v4
	v_cvt_u32_f32_e32 v4, v4
	v_mul_lo_u32 v1, v3, v4
	v_mul_hi_u32 v1, v4, v1
	v_add_u32_e32 v1, v4, v1
	v_mul_hi_u32 v1, v5, v1
	v_mul_lo_u32 v3, v1, v2
	v_sub_u32_e32 v3, v5, v3
	v_add_u32_e32 v4, 1, v1
	v_sub_u32_e32 v6, v3, v2
	v_cmp_ge_u32_e32 vcc, v3, v2
	s_nop 1
	v_cndmask_b32_e32 v1, v1, v4, vcc
	v_cndmask_b32_e32 v3, v3, v6, vcc
	v_add_u32_e32 v4, 1, v1
	v_cmp_ge_u32_e32 vcc, v3, v2
	v_add_u32_e32 v3, 1, v5
	s_nop 0
	v_cndmask_b32_e32 v1, v1, v4, vcc
	v_mul_lo_u32 v4, v2, v1
	v_add_u32_e32 v2, v4, v2
	v_cmp_ne_u32_e32 vcc, v3, v2
	s_and_saveexec_b64 s[2:3], vcc
	s_xor_b64 s[2:3], exec, s[2:3]
	s_cbranch_execz .LBB0_52
	s_waitcnt lgkmcnt(0)
	buffer_inv sc1
	global_load_dword v0, v177, s[20:21] sc1
	s_waitcnt vmcnt(0)
	v_cmp_eq_u32_e32 vcc, v0, v1
	s_and_saveexec_b64 s[4:5], vcc
	s_cbranch_execz .LBB0_51
	s_mov_b32 s16, 1
	s_mov_b64 s[6:7], 0
	s_branch .LBB0_42

.LBB0_52:
	s_andn2_saveexec_b64 s[2:3], s[2:3]
	s_cbranch_execz .LBB0_72
	s_mov_b64 s[2:3], exec
	buffer_wbl2 sc1
	s_waitcnt lgkmcnt(0)
	s_waitcnt vmcnt(0)
	buffer_inv sc1
	v_mbcnt_lo_u32_b32 v1, s2, 0
	v_mbcnt_hi_u32_b32 v1, s3, v1
	v_cmp_eq_u32_e32 vcc, 0, v1
	s_and_saveexec_b64 s[4:5], vcc
	s_cbranch_execz .LBB0_55
	s_bcnt1_i32_b64 s2, s[2:3]
	v_mov_b32_e32 v2, s2
	v_readlane_b32 s2, v251, 48
	v_readlane_b32 s3, v251, 49
	s_nop 4
	global_atomic_add v2, v177, v2, s[2:3] sc0

.LBB0_69:
	s_or_b64 exec, exec, s[2:3]
	s_mov_b64 s[2:3], exec
	v_mbcnt_lo_u32_b32 v0, s2, 0
	v_mbcnt_hi_u32_b32 v0, s3, v0
	v_cmp_eq_u32_e32 vcc, 0, v0
	s_waitcnt vmcnt(0)
	s_and_saveexec_b64 s[4:5], vcc
	s_cbranch_execz .LBB0_71
	s_bcnt1_i32_b64 s2, s[2:3]
	v_mov_b32_e32 v0, s2
	global_atomic_add v177, v0, s[20:21]
